# MLA loop: dead accumulator copies removed, softmax row sums via packed f32 add trees
# speedup vs baseline: 1.0093x; 1.0057x over previous
.LBB0_293:
	v_add3_u32 v205, v232, v231, v178
	v_exp_f32_e32 v115, v98
	v_exp_f32_e32 v124, v99
	v_exp_f32_e32 v125, v100
	v_exp_f32_e32 v126, v101
	ds_read_b128 v[98:101], v205 offset:21568
	v_exp_f32_e32 v127, v102
	v_exp_f32_e32 v128, v103
	v_exp_f32_e32 v129, v104
	v_exp_f32_e32 v172, v105
	v_exp_f32_e32 v173, v106
	v_exp_f32_e32 v174, v107
	v_exp_f32_e32 v202, v108
	v_exp_f32_e32 v203, v109
	v_cvt_pk_bf16_f32 v102, v115, v124
	v_cvt_pk_bf16_f32 v103, v125, v126
	v_cvt_pk_bf16_f32 v104, v127, v128
	v_cvt_pk_bf16_f32 v105, v129, v172
	ds_read_b128 v[106:109], v205 offset:21600
	ds_read_b128 v[116:119], v205 offset:26176
	ds_read_b128 v[120:123], v205 offset:26208
	s_waitcnt lgkmcnt(0)
	v_mfma_f32_32x32x16_bf16 v[34:49], v[98:101], v[102:105], v[34:49]
	v_exp_f32_e32 v204, v110
	v_exp_f32_e32 v212, v111
	v_exp_f32_e32 v213, v112
	v_exp_f32_e32 v214, v113
	v_cvt_pk_bf16_f32 v98, v173, v174
	v_cvt_pk_bf16_f32 v99, v202, v203
	v_cvt_pk_bf16_f32 v100, v204, v212
	v_cvt_pk_bf16_f32 v101, v213, v214
	ds_read_b128 v[110:113], v205 offset:30784
	v_cmp_eq_u32_e32 vcc, s60, v227
	v_mfma_f32_32x32x16_bf16 v[34:49], v[106:109], v[98:101], v[34:49]
	ds_read_b128 v[106:109], v205 offset:30816
	s_or_b64 s[40:41], vcc, s[40:41]
	s_mov_b64 s[26:27], 0
	v_mfma_f32_32x32x16_bf16 v[50:65], v[116:119], v[102:105], v[50:65]
	ds_read_b128 v[116:119], v205 offset:35392
	v_mfma_f32_32x32x16_bf16 v[50:65], v[120:123], v[98:101], v[50:65]
	ds_read_b128 v[120:123], v205 offset:35424
	s_waitcnt vmcnt(0)
	s_waitcnt lgkmcnt(0)
	s_barrier
	s_waitcnt lgkmcnt(0)
	v_mfma_f32_32x32x16_bf16 v[18:33], v[110:113], v[102:105], v[18:33]
	v_pk_add_f32 v[124:125], v[124:125], v[126:127]
	v_pk_add_f32 v[128:129], v[128:129], v[172:173]
	v_pk_add_f32 v[202:203], v[202:203], v[212:213]
	v_mfma_f32_32x32x16_bf16 v[2:17], v[116:119], v[102:105], v[2:17]
	v_mfma_f32_32x32x16_bf16 v[18:33], v[106:109], v[98:101], v[18:33]
	v_pk_add_f32 v[124:125], v[124:125], v[128:129]
	v_add_f32_e32 v110, v115, v174
	v_add_f32_e32 v111, v204, v214
	v_pk_add_f32 v[124:125], v[124:125], v[202:203]
	v_add_f32_e32 v110, v110, v111
	v_mfma_f32_32x32x16_bf16 v[2:17], v[120:123], v[98:101], v[2:17]
	v_add_f32_e32 v124, v124, v125
	v_add_f32_e32 v110, v110, v114
	v_add_f32_e32 v233, v124, v110
	s_andn2_b64 exec, exec, s[40:41]
	s_cbranch_execz .LBB0_310

.LBB0_304:
	v_add3_u32 v172, v232, v178, v231
	v_exp_f32_e32 v114, v66
	v_exp_f32_e32 v115, v67
	v_exp_f32_e32 v116, v68
	v_exp_f32_e32 v117, v69
	ds_read_b128 v[66:69], v172 offset:21504
	v_exp_f32_e32 v118, v70
	v_exp_f32_e32 v119, v71
	v_exp_f32_e32 v120, v72
	v_exp_f32_e32 v121, v73
	v_exp_f32_e32 v122, v74
	v_exp_f32_e32 v123, v75
	v_exp_f32_e32 v124, v76
	v_exp_f32_e32 v125, v77
	v_cvt_pk_bf16_f32 v70, v114, v115
	v_cvt_pk_bf16_f32 v71, v116, v117
	v_cvt_pk_bf16_f32 v72, v118, v119
	v_cvt_pk_bf16_f32 v73, v120, v121
	ds_read_b128 v[74:77], v172 offset:21536
	ds_read_b128 v[202:205], v172 offset:26112
	ds_read_b128 v[212:215], v172 offset:26144
	s_waitcnt lgkmcnt(0)
	v_mfma_f32_32x32x16_bf16 v[34:49], v[66:69], v[70:73], v[34:49]
	v_exp_f32_e32 v126, v78
	v_exp_f32_e32 v127, v79
	v_exp_f32_e32 v128, v80
	v_exp_f32_e32 v129, v81
	v_cvt_pk_bf16_f32 v66, v122, v123
	v_cvt_pk_bf16_f32 v67, v124, v125
	v_cvt_pk_bf16_f32 v68, v126, v127
	v_cvt_pk_bf16_f32 v69, v128, v129
	ds_read_b128 v[78:81], v172 offset:30720
	s_add_i32 s12, s61, 1
	v_mfma_f32_32x32x16_bf16 v[34:49], v[74:77], v[66:69], v[34:49]
	ds_read_b128 v[74:77], v172 offset:30752
	s_cmp_lg_u32 s61, 2
	s_cselect_b32 s61, s12, 0
	s_add_i32 s60, s60, 1
	v_cmp_lt_u32_e32 vcc, s60, v227
	v_mfma_f32_32x32x16_bf16 v[50:65], v[202:205], v[70:73], v[50:65]
	ds_read_b128 v[202:205], v172 offset:35328
	v_mfma_f32_32x32x16_bf16 v[50:65], v[212:215], v[66:69], v[50:65]
	ds_read_b128 v[212:215], v172 offset:35360
	s_waitcnt lgkmcnt(0)
	v_mfma_f32_32x32x16_bf16 v[18:33], v[78:81], v[70:73], v[18:33]
	v_mfma_f32_32x32x16_bf16 v[2:17], v[202:205], v[70:73], v[2:17]
	v_mfma_f32_32x32x16_bf16 v[18:33], v[74:77], v[66:69], v[18:33]
	v_mfma_f32_32x32x16_bf16 v[2:17], v[212:215], v[66:69], v[2:17]
	s_and_saveexec_b64 s[12:13], vcc
	s_cbranch_execz .LBB0_306
	s_mul_i32 s16, s61, 0x9c00
	v_add_u32_e32 v172, s16, v229
	ds_read_b128 v[202:205], v172
	ds_read_b128 v[212:215], v172 offset:32
	ds_read_b128 v[218:221], v172 offset:64
	ds_read_b128 v[222:225], v172 offset:96
	ds_read_b128 v[234:237], v172 offset:128
	s_waitcnt lgkmcnt(0)
	v_mfma_f32_32x32x16_bf16 v[66:81], v[202:205], v[130:133], v[82:97]
	ds_read_b128 v[202:205], v172 offset:160
	v_mfma_f32_32x32x16_bf16 v[66:81], v[212:215], v[134:137], v[66:81]
	ds_read_b128 v[212:215], v172 offset:192
	v_mfma_f32_32x32x16_bf16 v[66:81], v[218:221], v[138:141], v[66:81]
	ds_read_b128 v[218:221], v172 offset:224
	v_mfma_f32_32x32x16_bf16 v[66:81], v[222:225], v[142:145], v[66:81]
	ds_read_b128 v[222:225], v172 offset:256
	v_mfma_f32_32x32x16_bf16 v[66:81], v[234:237], v[146:149], v[66:81]
	ds_read_b128 v[234:237], v172 offset:288
	s_waitcnt lgkmcnt(0)
	v_mfma_f32_32x32x16_bf16 v[66:81], v[202:205], v[150:153], v[66:81]
	v_mfma_f32_32x32x16_bf16 v[66:81], v[212:215], v[154:157], v[66:81]
	v_mfma_f32_32x32x16_bf16 v[66:81], v[218:221], v[158:161], v[66:81]
	v_mfma_f32_32x32x16_bf16 v[66:81], v[222:225], v[162:165], v[66:81]
	v_mfma_f32_32x32x16_bf16 v[66:81], v[234:237], v[166:169], v[66:81]

.LBB0_308:
	s_or_b64 exec, exec, s[12:13]
	v_pk_add_f32 v[114:115], v[114:115], v[116:117]
	v_pk_add_f32 v[118:119], v[118:119], v[120:121]
	v_pk_add_f32 v[122:123], v[122:123], v[124:125]
	v_pk_add_f32 v[126:127], v[126:127], v[128:129]
	v_max_f32_e32 v116, v99, v99
	v_max_f32_e32 v117, v98, v98
	v_pk_add_f32 v[114:115], v[114:115], v[118:119]
	v_max_f32_e32 v116, v117, v116
	v_pk_add_f32 v[122:123], v[122:123], v[126:127]
	v_max3_f32 v116, v116, v100, v101
	v_max3_f32 v116, v116, v102, v103
	v_pk_add_f32 v[114:115], v[114:115], v[122:123]
	v_max3_f32 v116, v116, v104, v105
	v_max3_f32 v116, v116, v106, v107
	v_add_f32_e32 v114, v114, v115
	v_max3_f32 v116, v116, v108, v109
	v_max3_f32 v116, v116, v110, v111
	v_add_f32_e32 v114, v233, v114
	v_max3_f32 v115, v116, v112, v113
	v_cmp_lt_f32_e32 vcc, s30, v115
	s_cbranch_vccz .LBB0_293
	v_and_b32_e32 v117, 64, v210
	v_xor_b32_e32 v116, 32, v210
	v_add_u32_e32 v117, 64, v117
	v_cmp_lt_i32_e32 vcc, v116, v117
	s_nop 1
	v_cndmask_b32_e32 v116, v210, v116, vcc
	v_lshlrev_b32_e32 v116, 2, v116
	ds_bpermute_b32 v116, v116, v115
	s_waitcnt lgkmcnt(0)
	v_max3_f32 v116, v115, v116, 0
	v_exp_f32_e64 v118, -v116
	v_pk_add_f32 v[98:99], v[98:99], v[116:117] op_sel_hi:[1,0] neg_lo:[0,1] neg_hi:[0,1]
	v_pk_add_f32 v[100:101], v[100:101], v[116:117] op_sel_hi:[1,0] neg_lo:[0,1] neg_hi:[0,1]
	v_pk_add_f32 v[102:103], v[102:103], v[116:117] op_sel_hi:[1,0] neg_lo:[0,1] neg_hi:[0,1]
	v_pk_mul_f32 v[48:49], v[48:49], v[118:119] op_sel_hi:[1,0]
	v_pk_mul_f32 v[46:47], v[46:47], v[118:119] op_sel_hi:[1,0]
	v_pk_mul_f32 v[44:45], v[44:45], v[118:119] op_sel_hi:[1,0]
	v_pk_mul_f32 v[42:43], v[42:43], v[118:119] op_sel_hi:[1,0]
	v_pk_mul_f32 v[40:41], v[40:41], v[118:119] op_sel_hi:[1,0]
	v_pk_mul_f32 v[38:39], v[38:39], v[118:119] op_sel_hi:[1,0]
	v_pk_mul_f32 v[36:37], v[36:37], v[118:119] op_sel_hi:[1,0]
	v_pk_mul_f32 v[34:35], v[34:35], v[118:119] op_sel_hi:[1,0]
	v_pk_mul_f32 v[64:65], v[64:65], v[118:119] op_sel_hi:[1,0]
	v_pk_mul_f32 v[62:63], v[62:63], v[118:119] op_sel_hi:[1,0]
	v_pk_mul_f32 v[60:61], v[60:61], v[118:119] op_sel_hi:[1,0]
	v_pk_mul_f32 v[58:59], v[58:59], v[118:119] op_sel_hi:[1,0]
	v_pk_mul_f32 v[56:57], v[56:57], v[118:119] op_sel_hi:[1,0]
	v_pk_mul_f32 v[54:55], v[54:55], v[118:119] op_sel_hi:[1,0]
	v_pk_mul_f32 v[52:53], v[52:53], v[118:119] op_sel_hi:[1,0]
	v_pk_mul_f32 v[50:51], v[50:51], v[118:119] op_sel_hi:[1,0]
	v_pk_mul_f32 v[32:33], v[32:33], v[118:119] op_sel_hi:[1,0]
	v_pk_mul_f32 v[30:31], v[30:31], v[118:119] op_sel_hi:[1,0]
	v_pk_mul_f32 v[28:29], v[28:29], v[118:119] op_sel_hi:[1,0]
	v_pk_mul_f32 v[26:27], v[26:27], v[118:119] op_sel_hi:[1,0]
	v_pk_mul_f32 v[24:25], v[24:25], v[118:119] op_sel_hi:[1,0]
	v_pk_mul_f32 v[22:23], v[22:23], v[118:119] op_sel_hi:[1,0]
	v_pk_mul_f32 v[20:21], v[20:21], v[118:119] op_sel_hi:[1,0]
	v_pk_mul_f32 v[18:19], v[18:19], v[118:119] op_sel_hi:[1,0]
	v_pk_mul_f32 v[16:17], v[16:17], v[118:119] op_sel_hi:[1,0]
	v_pk_mul_f32 v[14:15], v[14:15], v[118:119] op_sel_hi:[1,0]
	v_pk_mul_f32 v[12:13], v[12:13], v[118:119] op_sel_hi:[1,0]
	v_pk_mul_f32 v[10:11], v[10:11], v[118:119] op_sel_hi:[1,0]
	v_pk_mul_f32 v[8:9], v[8:9], v[118:119] op_sel_hi:[1,0]
	v_pk_mul_f32 v[6:7], v[6:7], v[118:119] op_sel_hi:[1,0]
	v_pk_mul_f32 v[4:5], v[4:5], v[118:119] op_sel_hi:[1,0]
	v_pk_mul_f32 v[2:3], v[2:3], v[118:119] op_sel_hi:[1,0]
	v_pk_add_f32 v[104:105], v[104:105], v[116:117] op_sel_hi:[1,0] neg_lo:[0,1] neg_hi:[0,1]
	v_pk_add_f32 v[106:107], v[106:107], v[116:117] op_sel_hi:[1,0] neg_lo:[0,1] neg_hi:[0,1]
	v_pk_add_f32 v[108:109], v[108:109], v[116:117] op_sel_hi:[1,0] neg_lo:[0,1] neg_hi:[0,1]
	v_pk_add_f32 v[110:111], v[110:111], v[116:117] op_sel_hi:[1,0] neg_lo:[0,1] neg_hi:[0,1]
	v_pk_add_f32 v[112:113], v[112:113], v[116:117] op_sel_hi:[1,0] neg_lo:[0,1] neg_hi:[0,1]
	v_sub_f32_e32 v97, v97, v116
	v_sub_f32_e32 v96, v96, v116
	v_sub_f32_e32 v95, v95, v116
	v_sub_f32_e32 v94, v94, v116
	v_sub_f32_e32 v93, v93, v116
	v_sub_f32_e32 v92, v92, v116
	v_sub_f32_e32 v91, v91, v116
	v_sub_f32_e32 v90, v90, v116
	v_sub_f32_e32 v89, v89, v116
	v_sub_f32_e32 v88, v88, v116
	v_sub_f32_e32 v87, v87, v116
	v_sub_f32_e32 v86, v86, v116
	v_sub_f32_e32 v85, v85, v116
	v_sub_f32_e32 v84, v84, v116
	v_sub_f32_e32 v83, v83, v116
	v_sub_f32_e32 v82, v82, v116
	v_sub_f32_e32 v81, v81, v116
	v_sub_f32_e32 v80, v80, v116
	v_sub_f32_e32 v79, v79, v116
	v_sub_f32_e32 v78, v78, v116
	v_sub_f32_e32 v77, v77, v116
	v_sub_f32_e32 v76, v76, v116
	v_sub_f32_e32 v75, v75, v116
	v_sub_f32_e32 v74, v74, v116
	v_sub_f32_e32 v73, v73, v116
	v_sub_f32_e32 v72, v72, v116
	v_sub_f32_e32 v71, v71, v116
	v_sub_f32_e32 v70, v70, v116
	v_sub_f32_e32 v69, v69, v116
	v_sub_f32_e32 v68, v68, v116
	v_sub_f32_e32 v67, v67, v116
	v_sub_f32_e32 v66, v66, v116
	v_mul_f32_e32 v114, v114, v118
	s_branch .LBB0_293
